# EpiResidNorm part 2 (P4, P10): all twelve gain/scale/shift loads issued together at the start; column-half-1 no longer waits behind the half-0 H stores' acknowledgements
# baseline (speedup 1.0000x reference)
;     __device__ __forceinline__ void operator()(AccT& acc, const pg8::Unit& u, int wr, int wc, int fr_, int fq_) const {
;     ...
;         const float* sh = MODE == 0 ? shift + (size_t)bidx * NADA : nullptr;
; #pragma unroll
;         for (int bj = 0; bj < 2; ++bj) { const int col = u.pn * 256 + bj * 128 + wc * 32 + 8 * fq;
;             const f32x4 g0 = *(const f32x4*)(gvec + col), g1 = *(const f32x4*)(gvec + col + 4);
;             f32x4 a0 = g0, a1 = g1, b0 = {0.f, 0.f, 0.f, 0.f}, b1 = b0;
;             if (MODE == 0) { a0 = g0 * (*(const f32x4*)(sh + D + col) + 1.f); a1 = g1 * (*(const f32x4*)(sh + D + col + 4) + 1.f); b0 = *(const f32x4*)(sh + col); b1 = *(const f32x4*)(sh + col + 4); }
; #pragma unroll
;             for (int ai = 0; ai < 2; ++ai)
; #pragma unroll
;                 for (int m = 0; m < 4; ++m) { const int rl = ai * 128 + wr * 64 + m * 16 + fr; const size_t row = (size_t)u.pm * 256 + rl; const float rstd = sred[1024 + rl];
;                     const f32x4 y0 = acc[ai][bj][m][0] * rstd * a0 + b0, y1 = acc[ai][bj][m][1] * rstd * a1 + b1;
;                     if (MODE == 0) *(bf16x8*)(Hout + row * D + col) = pack8(y0[0], y0[1], y0[2], y0[3], y1[0], y1[1], y1[2], y1[3]);
;                     else { __builtin_nontemporal_store(y0, (f32x4*)(X + row * D + col)); __builtin_nontemporal_store(y1, (f32x4*)(X + row * D + col + 4)); }
;                     __builtin_amdgcn_sched_barrier(0); }
.LBB0_599:
	s_or_b64 exec, exec, s[4:5]
	s_add_u32 s6, s49, s6
	s_addc_u32 s7, s50, s7
	s_add_u32 s4, s6, 0x1000
	s_addc_u32 s5, s7, 0
	v_lshl_add_u64 v[130:131], s[4:5], 0, v[128:129]
	s_waitcnt lgkmcnt(0)
	s_barrier
	global_load_dwordx4 v[174:177], v[130:131], off
	global_load_dwordx4 v[178:181], v[130:131], off offset:16
	global_load_dwordx4 v[196:199], v[130:131], off offset:512
	global_load_dwordx4 v[200:203], v[130:131], off offset:528
	v_lshl_add_u64 v[156:157], s[16:17], 0, v[128:129]
	global_load_dwordx4 v[182:185], v[156:157], off
	global_load_dwordx4 v[186:189], v[156:157], off offset:16
	global_load_dwordx4 v[204:207], v[156:157], off offset:512
	global_load_dwordx4 v[208:211], v[156:157], off offset:528
	v_lshl_add_u64 v[158:159], s[6:7], 0, v[128:129]
	global_load_dwordx4 v[132:135], v[158:159], off
	global_load_dwordx4 v[222:225], v[158:159], off offset:512
	global_load_dwordx4 v[226:229], v[158:159], off offset:528
	global_load_dwordx4 v[128:131], v[158:159], off offset:16
	s_add_i32 s6, 0, 0x20000
	v_lshl_add_u32 v173, v152, 2, s6
	ds_read_b32 v192, v173 offset:4096
	v_lshlrev_b64 v[162:163], 19, v[162:163]
	v_ashrrev_i32_e32 v153, 31, v152
	v_lshl_add_u64 v[162:163], s[86:87], 0, v[162:163]
	v_lshlrev_b64 v[194:195], 11, v[152:153]
	s_waitcnt lgkmcnt(0)
	v_pk_mul_f32 v[58:59], v[58:59], v[192:193] op_sel_hi:[1,0]
	v_pk_mul_f32 v[56:57], v[56:57], v[192:193] op_sel_hi:[1,0]
	v_pk_mul_f32 v[62:63], v[62:63], v[192:193] op_sel_hi:[1,0]
	v_pk_mul_f32 v[60:61], v[60:61], v[192:193] op_sel_hi:[1,0]
	v_add_u32_e32 v160, 0x80, v154
	v_lshlrev_b64 v[154:155], 1, v[154:155]
	v_lshl_add_u64 v[194:195], v[162:163], 0, v[194:195]
	v_add_u32_e32 v190, 0x80, v152
	v_ashrrev_i32_e32 v161, 31, v160
	v_ashrrev_i32_e32 v191, 31, v190
	s_waitcnt vmcnt(11)
	v_pk_add_f32 v[176:177], v[176:177], 1.0 op_sel_hi:[1,0]
	v_pk_add_f32 v[174:175], v[174:175], 1.0 op_sel_hi:[1,0]
	s_waitcnt vmcnt(10)
	v_pk_add_f32 v[180:181], v[180:181], 1.0 op_sel_hi:[1,0]
	v_pk_add_f32 v[178:179], v[178:179], 1.0 op_sel_hi:[1,0]
	s_waitcnt vmcnt(7)
	v_pk_mul_f32 v[176:177], v[184:185], v[176:177]
	v_pk_mul_f32 v[174:175], v[182:183], v[174:175]
	s_waitcnt vmcnt(6)
	v_pk_mul_f32 v[180:181], v[188:189], v[180:181]
	v_pk_mul_f32 v[178:179], v[186:187], v[178:179]
	s_waitcnt vmcnt(3)
	v_pk_fma_f32 v[182:183], v[176:177], v[58:59], v[134:135]
	v_pk_fma_f32 v[56:57], v[174:175], v[56:57], v[132:133]
	s_waitcnt vmcnt(0)
	v_pk_fma_f32 v[62:63], v[180:181], v[62:63], v[130:131]
	v_pk_fma_f32 v[60:61], v[178:179], v[60:61], v[128:129]
	v_cvt_pk_bf16_f32 v58, v56, v57
	v_cvt_pk_bf16_f32 v59, v182, v183
	v_cvt_pk_bf16_f32 v60, v60, v61
	v_cvt_pk_bf16_f32 v61, v62, v63
	v_lshl_add_u64 v[56:57], v[194:195], 0, v[154:155]
	global_store_dwordx4 v[56:57], v[58:61], off
	ds_read_b32 v58, v173 offset:4160
	v_add_u32_e32 v182, 16, v152
	v_ashrrev_i32_e32 v183, 31, v182
	s_waitcnt lgkmcnt(0)
	v_pk_mul_f32 v[60:61], v[86:87], v[58:59] op_sel_hi:[1,0]
	v_pk_mul_f32 v[62:63], v[84:85], v[58:59] op_sel_hi:[1,0]
	v_pk_fma_f32 v[84:85], v[176:177], v[60:61], v[134:135]
	v_pk_fma_f32 v[60:61], v[174:175], v[62:63], v[132:133]
	v_pk_mul_f32 v[62:63], v[90:91], v[58:59] op_sel_hi:[1,0]
	v_pk_mul_f32 v[58:59], v[88:89], v[58:59] op_sel_hi:[1,0]
	v_pk_fma_f32 v[86:87], v[180:181], v[62:63], v[130:131]
	v_pk_fma_f32 v[58:59], v[178:179], v[58:59], v[128:129]
	v_cvt_pk_bf16_f32 v60, v60, v61
	v_cvt_pk_bf16_f32 v62, v58, v59
	v_lshlrev_b64 v[58:59], 11, v[182:183]
	v_lshl_add_u64 v[58:59], v[162:163], 0, v[58:59]
	v_cvt_pk_bf16_f32 v61, v84, v85
	v_cvt_pk_bf16_f32 v63, v86, v87
	v_lshl_add_u64 v[58:59], v[58:59], 0, v[154:155]
	global_store_dwordx4 v[58:59], v[60:63], off
	ds_read_b32 v60, v173 offset:4224
	s_nop 0
	v_add_u32_e32 v62, 32, v152
	v_ashrrev_i32_e32 v63, 31, v62
	s_waitcnt lgkmcnt(0)
	v_pk_mul_f32 v[84:85], v[114:115], v[60:61] op_sel_hi:[1,0]
	v_pk_mul_f32 v[86:87], v[112:113], v[60:61] op_sel_hi:[1,0]
	v_pk_fma_f32 v[88:89], v[176:177], v[84:85], v[134:135]
	v_pk_fma_f32 v[84:85], v[174:175], v[86:87], v[132:133]
	v_pk_mul_f32 v[86:87], v[118:119], v[60:61] op_sel_hi:[1,0]
	v_pk_mul_f32 v[60:61], v[116:117], v[60:61] op_sel_hi:[1,0]
	v_pk_fma_f32 v[90:91], v[180:181], v[86:87], v[130:131]
	v_pk_fma_f32 v[60:61], v[178:179], v[60:61], v[128:129]
	v_cvt_pk_bf16_f32 v84, v84, v85
	v_cvt_pk_bf16_f32 v86, v60, v61
	v_lshlrev_b64 v[60:61], 11, v[62:63]
	v_lshl_add_u64 v[60:61], v[162:163], 0, v[60:61]
	v_cvt_pk_bf16_f32 v85, v88, v89
	v_cvt_pk_bf16_f32 v87, v90, v91
	v_lshl_add_u64 v[60:61], v[60:61], 0, v[154:155]
	global_store_dwordx4 v[60:61], v[84:87], off
	ds_read_b32 v62, v173 offset:4288
	v_add_u32_e32 v88, 48, v152
	v_ashrrev_i32_e32 v89, 31, v88
	s_waitcnt lgkmcnt(0)
	v_pk_mul_f32 v[84:85], v[122:123], v[62:63] op_sel_hi:[1,0]
	v_pk_mul_f32 v[86:87], v[120:121], v[62:63] op_sel_hi:[1,0]
	v_pk_fma_f32 v[90:91], v[176:177], v[84:85], v[134:135]
	v_pk_fma_f32 v[84:85], v[174:175], v[86:87], v[132:133]
	v_pk_mul_f32 v[86:87], v[126:127], v[62:63] op_sel_hi:[1,0]
	v_pk_mul_f32 v[62:63], v[124:125], v[62:63] op_sel_hi:[1,0]
	v_pk_fma_f32 v[112:113], v[180:181], v[86:87], v[130:131]
	v_pk_fma_f32 v[62:63], v[178:179], v[62:63], v[128:129]
	v_cvt_pk_bf16_f32 v84, v84, v85
	v_cvt_pk_bf16_f32 v86, v62, v63
	v_lshlrev_b64 v[62:63], 11, v[88:89]
	v_lshl_add_u64 v[62:63], v[162:163], 0, v[62:63]
	v_cvt_pk_bf16_f32 v85, v90, v91
	v_cvt_pk_bf16_f32 v87, v112, v113
	v_lshl_add_u64 v[62:63], v[62:63], 0, v[154:155]
	global_store_dwordx4 v[62:63], v[84:87], off
	ds_read_b32 v84, v173 offset:4608
	s_waitcnt lgkmcnt(0)
;     __device__ __forceinline__ void operator()(AccT& acc, const pg8::Unit& u, int wr, int wc, int fr_, int fq_) const {
;     ...
;         const float* sh = MODE == 0 ? shift + (size_t)bidx * NADA : nullptr;
; #pragma unroll
;         for (int bj = 0; bj < 2; ++bj) { const int col = u.pn * 256 + bj * 128 + wc * 32 + 8 * fq;
;             const f32x4 g0 = *(const f32x4*)(gvec + col), g1 = *(const f32x4*)(gvec + col + 4);
;             f32x4 a0 = g0, a1 = g1, b0 = {0.f, 0.f, 0.f, 0.f}, b1 = b0;
;             if (MODE == 0) { a0 = g0 * (*(const f32x4*)(sh + D + col) + 1.f); a1 = g1 * (*(const f32x4*)(sh + D + col + 4) + 1.f); b0 = *(const f32x4*)(sh + col); b1 = *(const f32x4*)(sh + col + 4); }
; #pragma unroll
;             for (int ai = 0; ai < 2; ++ai)
; #pragma unroll
;                 for (int m = 0; m < 4; ++m) { const int rl = ai * 128 + wr * 64 + m * 16 + fr; const size_t row = (size_t)u.pm * 256 + rl; const float rstd = sred[1024 + rl];
;                     const f32x4 y0 = acc[ai][bj][m][0] * rstd * a0 + b0, y1 = acc[ai][bj][m][1] * rstd * a1 + b1;
;                     if (MODE == 0) *(bf16x8*)(Hout + row * D + col) = pack8(y0[0], y0[1], y0[2], y0[3], y1[0], y1[1], y1[2], y1[3]);
;                     else { __builtin_nontemporal_store(y0, (f32x4*)(X + row * D + col)); __builtin_nontemporal_store(y1, (f32x4*)(X + row * D + col + 4)); }
;                     __builtin_amdgcn_sched_barrier(0); }
	v_pk_mul_f32 v[86:87], v[110:111], v[84:85] op_sel_hi:[1,0]
	v_pk_mul_f32 v[88:89], v[108:109], v[84:85] op_sel_hi:[1,0]
	v_pk_mul_f32 v[90:91], v[102:103], v[84:85] op_sel_hi:[1,0]
	v_pk_mul_f32 v[84:85], v[100:101], v[84:85] op_sel_hi:[1,0]
	v_pk_fma_f32 v[100:101], v[176:177], v[86:87], v[134:135]
	v_pk_fma_f32 v[84:85], v[178:179], v[84:85], v[128:129]
	v_pk_fma_f32 v[86:87], v[174:175], v[88:89], v[132:133]
	v_cvt_pk_bf16_f32 v88, v84, v85
	v_lshlrev_b64 v[84:85], 11, v[190:191]
	v_pk_fma_f32 v[90:91], v[180:181], v[90:91], v[130:131]
	v_lshl_add_u64 v[84:85], v[162:163], 0, v[84:85]
	v_cvt_pk_bf16_f32 v86, v86, v87
	v_cvt_pk_bf16_f32 v87, v100, v101
	v_cvt_pk_bf16_f32 v89, v90, v91
	v_lshl_add_u64 v[84:85], v[84:85], 0, v[154:155]
	global_store_dwordx4 v[84:85], v[86:89], off
	ds_read_b32 v86, v173 offset:4672
	s_nop 0
	v_add_u32_e32 v88, 0x90, v152
	v_ashrrev_i32_e32 v89, 31, v88
	s_waitcnt lgkmcnt(0)
	v_pk_mul_f32 v[72:73], v[72:73], v[86:87] op_sel_hi:[1,0]
	v_pk_mul_f32 v[68:69], v[68:69], v[86:87] op_sel_hi:[1,0]
	v_pk_fma_f32 v[72:73], v[174:175], v[72:73], v[132:133]
	v_pk_mul_f32 v[70:71], v[70:71], v[86:87] op_sel_hi:[1,0]
	v_pk_fma_f32 v[68:69], v[178:179], v[68:69], v[128:129]
	v_pk_mul_f32 v[74:75], v[74:75], v[86:87] op_sel_hi:[1,0]
	v_pk_fma_f32 v[86:87], v[180:181], v[70:71], v[130:131]
	v_cvt_pk_bf16_f32 v70, v72, v73
	v_cvt_pk_bf16_f32 v72, v68, v69
	v_lshlrev_b64 v[68:69], 11, v[88:89]
	v_pk_fma_f32 v[74:75], v[176:177], v[74:75], v[134:135]
	v_lshl_add_u64 v[68:69], v[162:163], 0, v[68:69]
	v_cvt_pk_bf16_f32 v71, v74, v75
	v_cvt_pk_bf16_f32 v73, v86, v87
	v_lshl_add_u64 v[68:69], v[68:69], 0, v[154:155]
	global_store_dwordx4 v[68:69], v[70:73], off
	ds_read_b32 v70, v173 offset:4736
	s_nop 0
	v_add_u32_e32 v72, 0xa0, v152
	v_ashrrev_i32_e32 v73, 31, v72
	s_waitcnt lgkmcnt(0)
	v_pk_mul_f32 v[36:37], v[36:37], v[70:71] op_sel_hi:[1,0]
	v_pk_mul_f32 v[32:33], v[32:33], v[70:71] op_sel_hi:[1,0]
	v_pk_fma_f32 v[36:37], v[174:175], v[36:37], v[132:133]
	v_pk_mul_f32 v[34:35], v[34:35], v[70:71] op_sel_hi:[1,0]
	v_pk_fma_f32 v[32:33], v[178:179], v[32:33], v[128:129]
	v_pk_mul_f32 v[38:39], v[38:39], v[70:71] op_sel_hi:[1,0]
	v_pk_fma_f32 v[70:71], v[180:181], v[34:35], v[130:131]
	v_cvt_pk_bf16_f32 v34, v36, v37
	v_cvt_pk_bf16_f32 v36, v32, v33
	v_lshlrev_b64 v[32:33], 11, v[72:73]
	v_pk_fma_f32 v[38:39], v[176:177], v[38:39], v[134:135]
	v_lshl_add_u64 v[32:33], v[162:163], 0, v[32:33]
	v_cvt_pk_bf16_f32 v35, v38, v39
	v_cvt_pk_bf16_f32 v37, v70, v71
	v_lshl_add_u64 v[32:33], v[32:33], 0, v[154:155]
	global_store_dwordx4 v[32:33], v[34:37], off
	ds_read_b32 v34, v173 offset:4800
	s_nop 0
	v_add_u32_e32 v36, 0xb0, v152
	v_ashrrev_i32_e32 v37, 31, v36
	s_waitcnt lgkmcnt(0)
	v_pk_mul_f32 v[12:13], v[12:13], v[34:35] op_sel_hi:[1,0]
	s_nop 0
	v_pk_fma_f32 v[12:13], v[174:175], v[12:13], v[132:133]
	v_pk_mul_f32 v[10:11], v[10:11], v[34:35] op_sel_hi:[1,0]
	v_pk_mul_f32 v[8:9], v[8:9], v[34:35] op_sel_hi:[1,0]
	v_pk_mul_f32 v[14:15], v[14:15], v[34:35] op_sel_hi:[1,0]
	v_pk_fma_f32 v[34:35], v[180:181], v[10:11], v[130:131]
	v_pk_fma_f32 v[10:11], v[178:179], v[8:9], v[128:129]
	v_cvt_pk_bf16_f32 v8, v12, v13
	v_lshlrev_b64 v[12:13], 11, v[36:37]
	v_pk_fma_f32 v[14:15], v[176:177], v[14:15], v[134:135]
	v_lshl_add_u64 v[12:13], v[162:163], 0, v[12:13]
	v_cvt_pk_bf16_f32 v9, v14, v15
	v_cvt_pk_bf16_f32 v10, v10, v11
	v_cvt_pk_bf16_f32 v11, v34, v35
	v_lshl_add_u64 v[38:39], v[12:13], 0, v[154:155]
	global_store_dwordx4 v[38:39], v[8:11], off
	v_lshl_add_u64 v[12:13], v[160:161], 2, s[4:5]
	s_nop 0
	s_nop 0
	ds_read_b32 v74, v173 offset:4096
	s_waitcnt lgkmcnt(0)
	v_pk_mul_f32 v[22:23], v[22:23], v[74:75] op_sel_hi:[1,0]
	v_pk_mul_f32 v[20:21], v[20:21], v[74:75] op_sel_hi:[1,0]
	v_pk_mul_f32 v[30:31], v[30:31], v[74:75] op_sel_hi:[1,0]
	v_pk_mul_f32 v[28:29], v[28:29], v[74:75] op_sel_hi:[1,0]
	v_pk_add_f32 v[10:11], v[198:199], 1.0 op_sel_hi:[1,0]
	v_pk_add_f32 v[8:9], v[196:197], 1.0 op_sel_hi:[1,0]
	v_pk_add_f32 v[14:15], v[202:203], 1.0 op_sel_hi:[1,0]
	v_pk_add_f32 v[12:13], v[200:201], 1.0 op_sel_hi:[1,0]
	v_pk_mul_f32 v[36:37], v[206:207], v[10:11]
	v_pk_mul_f32 v[34:35], v[204:205], v[8:9]
	v_pk_mul_f32 v[14:15], v[210:211], v[14:15]
	v_pk_mul_f32 v[12:13], v[208:209], v[12:13]
	v_pk_fma_f32 v[10:11], v[36:37], v[22:23], v[224:225]
	v_pk_fma_f32 v[8:9], v[34:35], v[20:21], v[222:223]
	v_pk_fma_f32 v[20:21], v[14:15], v[30:31], v[228:229]
	v_pk_fma_f32 v[22:23], v[12:13], v[28:29], v[226:227]
	v_cvt_pk_bf16_f32 v8, v8, v9
	v_cvt_pk_bf16_f32 v9, v10, v11
	v_cvt_pk_bf16_f32 v10, v22, v23
	v_cvt_pk_bf16_f32 v11, v20, v21
	global_store_dwordx4 v[56:57], v[8:11], off offset:256
	ds_read_b32 v8, v173 offset:4160
	s_waitcnt lgkmcnt(0)
;     __device__ __forceinline__ void operator()(AccT& acc, const pg8::Unit& u, int wr, int wc, int fr_, int fq_) const {
;     ...
; #pragma unroll
;             for (int ai = 0; ai < 2; ++ai)
; #pragma unroll
;                 for (int m = 0; m < 4; ++m) { const int rl = ai * 128 + wr * 64 + m * 16 + fr; const size_t row = (size_t)u.pm * 256 + rl; const float rstd = sred[1024 + rl];
;                     const f32x4 y0 = acc[ai][bj][m][0] * rstd * a0 + b0, y1 = acc[ai][bj][m][1] * rstd * a1 + b1;
;                     if (MODE == 0) *(bf16x8*)(Hout + row * D + col) = pack8(y0[0], y0[1], y0[2], y0[3], y1[0], y1[1], y1[2], y1[3]);
;                     else { __builtin_nontemporal_store(y0, (f32x4*)(X + row * D + col)); __builtin_nontemporal_store(y1, (f32x4*)(X + row * D + col + 4)); }
;                     __builtin_amdgcn_sched_barrier(0); }
;         }
;         __syncthreads();
	v_pk_mul_f32 v[10:11], v[42:43], v[8:9] op_sel_hi:[1,0]
	v_pk_mul_f32 v[20:21], v[40:41], v[8:9] op_sel_hi:[1,0]
	v_pk_mul_f32 v[22:23], v[50:51], v[8:9] op_sel_hi:[1,0]
	v_pk_mul_f32 v[8:9], v[48:49], v[8:9] op_sel_hi:[1,0]
	v_pk_fma_f32 v[10:11], v[36:37], v[10:11], v[224:225]
	v_pk_fma_f32 v[20:21], v[34:35], v[20:21], v[222:223]
	v_pk_fma_f32 v[22:23], v[14:15], v[22:23], v[228:229]
	v_pk_fma_f32 v[28:29], v[12:13], v[8:9], v[226:227]
	v_cvt_pk_bf16_f32 v8, v20, v21
	v_cvt_pk_bf16_f32 v9, v10, v11
	v_cvt_pk_bf16_f32 v10, v28, v29
	v_cvt_pk_bf16_f32 v11, v22, v23
	global_store_dwordx4 v[58:59], v[8:11], off offset:256
	ds_read_b32 v8, v173 offset:4224
	s_waitcnt lgkmcnt(0)
	v_pk_mul_f32 v[10:11], v[66:67], v[8:9] op_sel_hi:[1,0]
	v_pk_mul_f32 v[20:21], v[64:65], v[8:9] op_sel_hi:[1,0]
	v_pk_mul_f32 v[22:23], v[82:83], v[8:9] op_sel_hi:[1,0]
	v_pk_mul_f32 v[8:9], v[80:81], v[8:9] op_sel_hi:[1,0]
	v_pk_fma_f32 v[10:11], v[36:37], v[10:11], v[224:225]
	v_pk_fma_f32 v[20:21], v[34:35], v[20:21], v[222:223]
	v_pk_fma_f32 v[22:23], v[14:15], v[22:23], v[228:229]
	v_pk_fma_f32 v[28:29], v[12:13], v[8:9], v[226:227]
	v_cvt_pk_bf16_f32 v8, v20, v21
	v_cvt_pk_bf16_f32 v9, v10, v11
	v_cvt_pk_bf16_f32 v10, v28, v29
	v_cvt_pk_bf16_f32 v11, v22, v23
	global_store_dwordx4 v[60:61], v[8:11], off offset:256
	ds_read_b32 v8, v173 offset:4288
	s_waitcnt lgkmcnt(0)
	v_pk_mul_f32 v[10:11], v[98:99], v[8:9] op_sel_hi:[1,0]
	v_pk_mul_f32 v[20:21], v[96:97], v[8:9] op_sel_hi:[1,0]
	v_pk_mul_f32 v[22:23], v[106:107], v[8:9] op_sel_hi:[1,0]
	v_pk_mul_f32 v[8:9], v[104:105], v[8:9] op_sel_hi:[1,0]
	v_pk_fma_f32 v[10:11], v[36:37], v[10:11], v[224:225]
	v_pk_fma_f32 v[20:21], v[34:35], v[20:21], v[222:223]
	v_pk_fma_f32 v[22:23], v[14:15], v[22:23], v[228:229]
	v_pk_fma_f32 v[28:29], v[12:13], v[8:9], v[226:227]
	v_cvt_pk_bf16_f32 v8, v20, v21
	v_cvt_pk_bf16_f32 v9, v10, v11
	v_cvt_pk_bf16_f32 v10, v28, v29
	v_cvt_pk_bf16_f32 v11, v22, v23
	global_store_dwordx4 v[62:63], v[8:11], off offset:256
	ds_read_b32 v8, v173 offset:4608
	s_waitcnt lgkmcnt(0)
	v_pk_mul_f32 v[10:11], v[94:95], v[8:9] op_sel_hi:[1,0]
	v_pk_mul_f32 v[20:21], v[92:93], v[8:9] op_sel_hi:[1,0]
	v_pk_mul_f32 v[22:23], v[78:79], v[8:9] op_sel_hi:[1,0]
	v_pk_mul_f32 v[8:9], v[76:77], v[8:9] op_sel_hi:[1,0]
	v_pk_fma_f32 v[10:11], v[36:37], v[10:11], v[224:225]
	v_pk_fma_f32 v[20:21], v[34:35], v[20:21], v[222:223]
	v_pk_fma_f32 v[22:23], v[14:15], v[22:23], v[228:229]
	v_pk_fma_f32 v[28:29], v[12:13], v[8:9], v[226:227]
	v_cvt_pk_bf16_f32 v8, v20, v21
	v_cvt_pk_bf16_f32 v9, v10, v11
	v_cvt_pk_bf16_f32 v10, v28, v29
	v_cvt_pk_bf16_f32 v11, v22, v23
	global_store_dwordx4 v[84:85], v[8:11], off offset:256
	ds_read_b32 v8, v173 offset:4672
	s_waitcnt lgkmcnt(0)
	v_pk_mul_f32 v[10:11], v[54:55], v[8:9] op_sel_hi:[1,0]
	v_pk_mul_f32 v[20:21], v[52:53], v[8:9] op_sel_hi:[1,0]
	v_pk_mul_f32 v[22:23], v[46:47], v[8:9] op_sel_hi:[1,0]
	v_pk_mul_f32 v[8:9], v[44:45], v[8:9] op_sel_hi:[1,0]
	v_pk_fma_f32 v[10:11], v[36:37], v[10:11], v[224:225]
	v_pk_fma_f32 v[20:21], v[34:35], v[20:21], v[222:223]
	v_pk_fma_f32 v[22:23], v[14:15], v[22:23], v[228:229]
	v_pk_fma_f32 v[28:29], v[12:13], v[8:9], v[226:227]
	v_cvt_pk_bf16_f32 v8, v20, v21
	v_cvt_pk_bf16_f32 v9, v10, v11
	v_cvt_pk_bf16_f32 v10, v28, v29
	v_cvt_pk_bf16_f32 v11, v22, v23
	global_store_dwordx4 v[68:69], v[8:11], off offset:256
	ds_read_b32 v8, v173 offset:4736
	s_waitcnt lgkmcnt(0)
	v_pk_mul_f32 v[10:11], v[26:27], v[8:9] op_sel_hi:[1,0]
	v_pk_mul_f32 v[20:21], v[24:25], v[8:9] op_sel_hi:[1,0]
	v_pk_mul_f32 v[18:19], v[18:19], v[8:9] op_sel_hi:[1,0]
	v_pk_mul_f32 v[8:9], v[16:17], v[8:9] op_sel_hi:[1,0]
	v_pk_fma_f32 v[10:11], v[36:37], v[10:11], v[224:225]
	v_pk_fma_f32 v[16:17], v[34:35], v[20:21], v[222:223]
	v_pk_fma_f32 v[18:19], v[14:15], v[18:19], v[228:229]
	v_pk_fma_f32 v[20:21], v[12:13], v[8:9], v[226:227]
	v_cvt_pk_bf16_f32 v8, v16, v17
	v_cvt_pk_bf16_f32 v9, v10, v11
	v_cvt_pk_bf16_f32 v10, v20, v21
	v_cvt_pk_bf16_f32 v11, v18, v19
	global_store_dwordx4 v[32:33], v[8:11], off offset:256
	ds_read_b32 v8, v173 offset:4800
	s_waitcnt lgkmcnt(0)
	v_pk_mul_f32 v[6:7], v[6:7], v[8:9] op_sel_hi:[1,0]
	v_pk_mul_f32 v[4:5], v[4:5], v[8:9] op_sel_hi:[1,0]
	v_pk_mul_f32 v[2:3], v[2:3], v[8:9] op_sel_hi:[1,0]
	v_pk_mul_f32 v[0:1], v[0:1], v[8:9] op_sel_hi:[1,0]
	v_pk_fma_f32 v[6:7], v[36:37], v[6:7], v[224:225]
	v_pk_fma_f32 v[4:5], v[34:35], v[4:5], v[222:223]
	v_pk_fma_f32 v[8:9], v[14:15], v[2:3], v[228:229]
	v_pk_fma_f32 v[2:3], v[12:13], v[0:1], v[226:227]
	v_cvt_pk_bf16_f32 v0, v4, v5
	v_cvt_pk_bf16_f32 v1, v6, v7
	v_cvt_pk_bf16_f32 v2, v2, v3
	v_cvt_pk_bf16_f32 v3, v8, v9
	global_store_dwordx4 v[38:39], v[0:3], off offset:256
	s_and_b64 vcc, exec, s[8:9]
	s_mov_b64 s[4:5], -1
	s_barrier
	s_cbranch_vccnz .LBB0_561
	s_andn2_b64 vcc, exec, s[18:19]
	s_cbranch_vccnz .LBB0_560
	s_barrier
	s_branch .LBB0_560

;     __device__ __forceinline__ void operator()(AccT& acc, const pg8::Unit& u, int wr, int wc, int fr_, int fq_) const {
;     ...
;         const float* sh = MODE == 0 ? shift + (size_t)bidx * NADA : nullptr;
; #pragma unroll
;         for (int bj = 0; bj < 2; ++bj) { const int col = u.pn * 256 + bj * 128 + wc * 32 + 8 * fq;
;             const f32x4 g0 = *(const f32x4*)(gvec + col), g1 = *(const f32x4*)(gvec + col + 4);
;             f32x4 a0 = g0, a1 = g1, b0 = {0.f, 0.f, 0.f, 0.f}, b1 = b0;
;             if (MODE == 0) { a0 = g0 * (*(const f32x4*)(sh + D + col) + 1.f); a1 = g1 * (*(const f32x4*)(sh + D + col + 4) + 1.f); b0 = *(const f32x4*)(sh + col); b1 = *(const f32x4*)(sh + col + 4); }
; #pragma unroll
;             for (int ai = 0; ai < 2; ++ai)
; #pragma unroll
;                 for (int m = 0; m < 4; ++m) { const int rl = ai * 128 + wr * 64 + m * 16 + fr; const size_t row = (size_t)u.pm * 256 + rl; const float rstd = sred[1024 + rl];
;                     const f32x4 y0 = acc[ai][bj][m][0] * rstd * a0 + b0, y1 = acc[ai][bj][m][1] * rstd * a1 + b1;
;                     if (MODE == 0) *(bf16x8*)(Hout + row * D + col) = pack8(y0[0], y0[1], y0[2], y0[3], y1[0], y1[1], y1[2], y1[3]);
;                     else { __builtin_nontemporal_store(y0, (f32x4*)(X + row * D + col)); __builtin_nontemporal_store(y1, (f32x4*)(X + row * D + col + 4)); }
;                     __builtin_amdgcn_sched_barrier(0); }
.LBB0_2040:
	s_or_b64 exec, exec, s[4:5]
	s_add_u32 s6, s50, s6
	s_addc_u32 s7, s51, s7
	s_add_u32 s4, s6, 0x1000
	s_addc_u32 s5, s7, 0
	v_lshl_add_u64 v[130:131], s[4:5], 0, v[128:129]
	s_waitcnt lgkmcnt(0)
	s_barrier
	global_load_dwordx4 v[174:177], v[130:131], off
	global_load_dwordx4 v[178:181], v[130:131], off offset:16
	global_load_dwordx4 v[196:199], v[130:131], off offset:512
	global_load_dwordx4 v[200:203], v[130:131], off offset:528
	v_lshl_add_u64 v[156:157], s[16:17], 0, v[128:129]
	global_load_dwordx4 v[182:185], v[156:157], off
	global_load_dwordx4 v[186:189], v[156:157], off offset:16
	global_load_dwordx4 v[204:207], v[156:157], off offset:512
	global_load_dwordx4 v[208:211], v[156:157], off offset:528
	v_lshl_add_u64 v[158:159], s[6:7], 0, v[128:129]
	global_load_dwordx4 v[132:135], v[158:159], off
	global_load_dwordx4 v[222:225], v[158:159], off offset:512
	global_load_dwordx4 v[226:229], v[158:159], off offset:528
	global_load_dwordx4 v[128:131], v[158:159], off offset:16
	s_add_i32 s6, 0, 0x20000
	v_lshl_add_u32 v173, v152, 2, s6
	ds_read_b32 v192, v173 offset:4096
	v_lshlrev_b64 v[162:163], 19, v[162:163]
	v_ashrrev_i32_e32 v153, 31, v152
	v_lshl_add_u64 v[162:163], s[86:87], 0, v[162:163]
	v_lshlrev_b64 v[194:195], 11, v[152:153]
	s_waitcnt lgkmcnt(0)
	v_pk_mul_f32 v[58:59], v[58:59], v[192:193] op_sel_hi:[1,0]
	v_pk_mul_f32 v[56:57], v[56:57], v[192:193] op_sel_hi:[1,0]
	v_pk_mul_f32 v[66:67], v[66:67], v[192:193] op_sel_hi:[1,0]
	v_pk_mul_f32 v[64:65], v[64:65], v[192:193] op_sel_hi:[1,0]
	v_add_u32_e32 v160, 0x80, v154
	v_lshlrev_b64 v[154:155], 1, v[154:155]
	v_lshl_add_u64 v[194:195], v[162:163], 0, v[194:195]
	v_add_u32_e32 v190, 0x80, v152
	v_ashrrev_i32_e32 v161, 31, v160
	v_ashrrev_i32_e32 v191, 31, v190
	s_waitcnt vmcnt(11)
	v_pk_add_f32 v[176:177], v[176:177], 1.0 op_sel_hi:[1,0]
	v_pk_add_f32 v[174:175], v[174:175], 1.0 op_sel_hi:[1,0]
	s_waitcnt vmcnt(10)
	v_pk_add_f32 v[180:181], v[180:181], 1.0 op_sel_hi:[1,0]
	v_pk_add_f32 v[178:179], v[178:179], 1.0 op_sel_hi:[1,0]
	s_waitcnt vmcnt(7)
	v_pk_mul_f32 v[176:177], v[184:185], v[176:177]
	v_pk_mul_f32 v[174:175], v[182:183], v[174:175]
	s_waitcnt vmcnt(6)
	v_pk_mul_f32 v[180:181], v[188:189], v[180:181]
	v_pk_mul_f32 v[178:179], v[186:187], v[178:179]
	s_waitcnt vmcnt(3)
	v_pk_fma_f32 v[58:59], v[176:177], v[58:59], v[134:135]
	v_pk_fma_f32 v[56:57], v[174:175], v[56:57], v[132:133]
	s_waitcnt vmcnt(0)
	v_pk_fma_f32 v[182:183], v[180:181], v[66:67], v[130:131]
	v_pk_fma_f32 v[66:67], v[178:179], v[64:65], v[128:129]
	v_cvt_pk_bf16_f32 v64, v56, v57
	v_cvt_pk_bf16_f32 v65, v58, v59
	v_cvt_pk_bf16_f32 v66, v66, v67
	v_cvt_pk_bf16_f32 v67, v182, v183
	v_lshl_add_u64 v[56:57], v[194:195], 0, v[154:155]
	global_store_dwordx4 v[56:57], v[64:67], off
	ds_read_b32 v58, v173 offset:4160
	v_add_u32_e32 v182, 16, v152
	v_ashrrev_i32_e32 v183, 31, v182
	s_waitcnt lgkmcnt(0)
	v_pk_mul_f32 v[64:65], v[86:87], v[58:59] op_sel_hi:[1,0]
	v_pk_mul_f32 v[66:67], v[84:85], v[58:59] op_sel_hi:[1,0]
	v_pk_fma_f32 v[84:85], v[176:177], v[64:65], v[134:135]
	v_pk_fma_f32 v[64:65], v[174:175], v[66:67], v[132:133]
	v_pk_mul_f32 v[66:67], v[94:95], v[58:59] op_sel_hi:[1,0]
	v_pk_mul_f32 v[58:59], v[92:93], v[58:59] op_sel_hi:[1,0]
	v_pk_fma_f32 v[86:87], v[180:181], v[66:67], v[130:131]
	v_pk_fma_f32 v[58:59], v[178:179], v[58:59], v[128:129]
	v_cvt_pk_bf16_f32 v64, v64, v65
	v_cvt_pk_bf16_f32 v66, v58, v59
	v_lshlrev_b64 v[58:59], 11, v[182:183]
	v_lshl_add_u64 v[58:59], v[162:163], 0, v[58:59]
	v_cvt_pk_bf16_f32 v65, v84, v85
	v_cvt_pk_bf16_f32 v67, v86, v87
	v_lshl_add_u64 v[58:59], v[58:59], 0, v[154:155]
	global_store_dwordx4 v[58:59], v[64:67], off
	ds_read_b32 v64, v173 offset:4224
	s_nop 0
	v_add_u32_e32 v66, 32, v152
	v_ashrrev_i32_e32 v67, 31, v66
	s_waitcnt lgkmcnt(0)
	v_pk_mul_f32 v[84:85], v[114:115], v[64:65] op_sel_hi:[1,0]
	v_pk_mul_f32 v[86:87], v[112:113], v[64:65] op_sel_hi:[1,0]
	v_pk_fma_f32 v[92:93], v[176:177], v[84:85], v[134:135]
	v_pk_fma_f32 v[84:85], v[174:175], v[86:87], v[132:133]
	v_pk_mul_f32 v[86:87], v[118:119], v[64:65] op_sel_hi:[1,0]
	v_pk_mul_f32 v[64:65], v[116:117], v[64:65] op_sel_hi:[1,0]
	v_pk_fma_f32 v[94:95], v[180:181], v[86:87], v[130:131]
	v_pk_fma_f32 v[64:65], v[178:179], v[64:65], v[128:129]
	v_cvt_pk_bf16_f32 v84, v84, v85
	v_cvt_pk_bf16_f32 v86, v64, v65
	v_lshlrev_b64 v[64:65], 11, v[66:67]
	v_lshl_add_u64 v[64:65], v[162:163], 0, v[64:65]
	v_cvt_pk_bf16_f32 v85, v92, v93
	v_cvt_pk_bf16_f32 v87, v94, v95
	v_lshl_add_u64 v[64:65], v[64:65], 0, v[154:155]
	global_store_dwordx4 v[64:65], v[84:87], off
	ds_read_b32 v66, v173 offset:4288
	v_add_u32_e32 v92, 48, v152
	v_ashrrev_i32_e32 v93, 31, v92
	s_waitcnt lgkmcnt(0)
	v_pk_mul_f32 v[84:85], v[122:123], v[66:67] op_sel_hi:[1,0]
	v_pk_mul_f32 v[86:87], v[120:121], v[66:67] op_sel_hi:[1,0]
	v_pk_fma_f32 v[94:95], v[176:177], v[84:85], v[134:135]
	v_pk_fma_f32 v[84:85], v[174:175], v[86:87], v[132:133]
	v_pk_mul_f32 v[86:87], v[126:127], v[66:67] op_sel_hi:[1,0]
	v_pk_mul_f32 v[66:67], v[124:125], v[66:67] op_sel_hi:[1,0]
	v_pk_fma_f32 v[112:113], v[180:181], v[86:87], v[130:131]
	v_pk_fma_f32 v[66:67], v[178:179], v[66:67], v[128:129]
	v_cvt_pk_bf16_f32 v84, v84, v85
	v_cvt_pk_bf16_f32 v86, v66, v67
	v_lshlrev_b64 v[66:67], 11, v[92:93]
	v_lshl_add_u64 v[66:67], v[162:163], 0, v[66:67]
	v_cvt_pk_bf16_f32 v85, v94, v95
	v_cvt_pk_bf16_f32 v87, v112, v113
	v_lshl_add_u64 v[66:67], v[66:67], 0, v[154:155]
	global_store_dwordx4 v[66:67], v[84:87], off
	ds_read_b32 v84, v173 offset:4608
	s_waitcnt lgkmcnt(0)
;     __device__ __forceinline__ void operator()(AccT& acc, const pg8::Unit& u, int wr, int wc, int fr_, int fq_) const {
;     ...
;         const float* sh = MODE == 0 ? shift + (size_t)bidx * NADA : nullptr;
; #pragma unroll
;         for (int bj = 0; bj < 2; ++bj) { const int col = u.pn * 256 + bj * 128 + wc * 32 + 8 * fq;
;             const f32x4 g0 = *(const f32x4*)(gvec + col), g1 = *(const f32x4*)(gvec + col + 4);
;             f32x4 a0 = g0, a1 = g1, b0 = {0.f, 0.f, 0.f, 0.f}, b1 = b0;
;             if (MODE == 0) { a0 = g0 * (*(const f32x4*)(sh + D + col) + 1.f); a1 = g1 * (*(const f32x4*)(sh + D + col + 4) + 1.f); b0 = *(const f32x4*)(sh + col); b1 = *(const f32x4*)(sh + col + 4); }
; #pragma unroll
;             for (int ai = 0; ai < 2; ++ai)
; #pragma unroll
;                 for (int m = 0; m < 4; ++m) { const int rl = ai * 128 + wr * 64 + m * 16 + fr; const size_t row = (size_t)u.pm * 256 + rl; const float rstd = sred[1024 + rl];
;                     const f32x4 y0 = acc[ai][bj][m][0] * rstd * a0 + b0, y1 = acc[ai][bj][m][1] * rstd * a1 + b1;
;                     if (MODE == 0) *(bf16x8*)(Hout + row * D + col) = pack8(y0[0], y0[1], y0[2], y0[3], y1[0], y1[1], y1[2], y1[3]);
;                     else { __builtin_nontemporal_store(y0, (f32x4*)(X + row * D + col)); __builtin_nontemporal_store(y1, (f32x4*)(X + row * D + col + 4)); }
;                     __builtin_amdgcn_sched_barrier(0); }
	v_pk_mul_f32 v[86:87], v[110:111], v[84:85] op_sel_hi:[1,0]
	v_pk_mul_f32 v[92:93], v[108:109], v[84:85] op_sel_hi:[1,0]
	v_pk_mul_f32 v[94:95], v[102:103], v[84:85] op_sel_hi:[1,0]
	v_pk_mul_f32 v[84:85], v[100:101], v[84:85] op_sel_hi:[1,0]
	v_pk_fma_f32 v[100:101], v[180:181], v[94:95], v[130:131]
	v_pk_fma_f32 v[84:85], v[178:179], v[84:85], v[128:129]
	v_pk_fma_f32 v[86:87], v[176:177], v[86:87], v[134:135]
	v_cvt_pk_bf16_f32 v94, v84, v85
	v_lshlrev_b64 v[84:85], 11, v[190:191]
	v_pk_fma_f32 v[92:93], v[174:175], v[92:93], v[132:133]
	v_lshl_add_u64 v[84:85], v[162:163], 0, v[84:85]
	v_cvt_pk_bf16_f32 v92, v92, v93
	v_cvt_pk_bf16_f32 v93, v86, v87
	v_cvt_pk_bf16_f32 v95, v100, v101
	v_lshl_add_u64 v[84:85], v[84:85], 0, v[154:155]
	global_store_dwordx4 v[84:85], v[92:95], off
	ds_read_b32 v86, v173 offset:4672
	s_nop 0
	v_add_u32_e32 v92, 0x90, v152
	v_ashrrev_i32_e32 v93, 31, v92
	s_waitcnt lgkmcnt(0)
	v_pk_mul_f32 v[72:73], v[72:73], v[86:87] op_sel_hi:[1,0]
	v_pk_mul_f32 v[68:69], v[68:69], v[86:87] op_sel_hi:[1,0]
	v_pk_fma_f32 v[72:73], v[174:175], v[72:73], v[132:133]
	v_pk_mul_f32 v[70:71], v[70:71], v[86:87] op_sel_hi:[1,0]
	v_pk_fma_f32 v[68:69], v[178:179], v[68:69], v[128:129]
	v_pk_mul_f32 v[74:75], v[74:75], v[86:87] op_sel_hi:[1,0]
	v_pk_fma_f32 v[86:87], v[180:181], v[70:71], v[130:131]
	v_cvt_pk_bf16_f32 v70, v72, v73
	v_cvt_pk_bf16_f32 v72, v68, v69
	v_lshlrev_b64 v[68:69], 11, v[92:93]
	v_pk_fma_f32 v[74:75], v[176:177], v[74:75], v[134:135]
	v_lshl_add_u64 v[68:69], v[162:163], 0, v[68:69]
	v_cvt_pk_bf16_f32 v71, v74, v75
	v_cvt_pk_bf16_f32 v73, v86, v87
	v_lshl_add_u64 v[68:69], v[68:69], 0, v[154:155]
	global_store_dwordx4 v[68:69], v[70:73], off
	ds_read_b32 v70, v173 offset:4736
	s_nop 0
	v_add_u32_e32 v72, 0xa0, v152
	v_ashrrev_i32_e32 v73, 31, v72
	s_waitcnt lgkmcnt(0)
	v_pk_mul_f32 v[42:43], v[42:43], v[70:71] op_sel_hi:[1,0]
	v_pk_mul_f32 v[40:41], v[40:41], v[70:71] op_sel_hi:[1,0]
	v_pk_mul_f32 v[32:33], v[32:33], v[70:71] op_sel_hi:[1,0]
	v_pk_fma_f32 v[42:43], v[176:177], v[42:43], v[134:135]
	v_pk_fma_f32 v[40:41], v[174:175], v[40:41], v[132:133]
	v_pk_fma_f32 v[32:33], v[178:179], v[32:33], v[128:129]
	v_pk_mul_f32 v[34:35], v[34:35], v[70:71] op_sel_hi:[1,0]
	v_cvt_pk_bf16_f32 v40, v40, v41
	v_cvt_pk_bf16_f32 v41, v42, v43
	v_cvt_pk_bf16_f32 v42, v32, v33
	v_lshlrev_b64 v[32:33], 11, v[72:73]
	v_pk_fma_f32 v[34:35], v[180:181], v[34:35], v[130:131]
	v_lshl_add_u64 v[32:33], v[162:163], 0, v[32:33]
	v_cvt_pk_bf16_f32 v43, v34, v35
	v_lshl_add_u64 v[32:33], v[32:33], 0, v[154:155]
	global_store_dwordx4 v[32:33], v[40:43], off
	ds_read_b32 v34, v173 offset:4800
	s_nop 0
	v_add_u32_e32 v40, 0xb0, v152
	v_ashrrev_i32_e32 v41, 31, v40
	s_waitcnt lgkmcnt(0)
	v_pk_mul_f32 v[12:13], v[12:13], v[34:35] op_sel_hi:[1,0]
	s_nop 0
	v_pk_fma_f32 v[12:13], v[174:175], v[12:13], v[132:133]
	v_pk_mul_f32 v[10:11], v[10:11], v[34:35] op_sel_hi:[1,0]
	v_pk_mul_f32 v[8:9], v[8:9], v[34:35] op_sel_hi:[1,0]
	v_pk_mul_f32 v[14:15], v[14:15], v[34:35] op_sel_hi:[1,0]
	v_pk_fma_f32 v[34:35], v[180:181], v[10:11], v[130:131]
	v_pk_fma_f32 v[10:11], v[178:179], v[8:9], v[128:129]
	v_cvt_pk_bf16_f32 v8, v12, v13
	v_lshlrev_b64 v[12:13], 11, v[40:41]
	v_pk_fma_f32 v[14:15], v[176:177], v[14:15], v[134:135]
	v_lshl_add_u64 v[12:13], v[162:163], 0, v[12:13]
	v_cvt_pk_bf16_f32 v9, v14, v15
	v_cvt_pk_bf16_f32 v10, v10, v11
	v_cvt_pk_bf16_f32 v11, v34, v35
	v_lshl_add_u64 v[34:35], v[12:13], 0, v[154:155]
	global_store_dwordx4 v[34:35], v[8:11], off
	v_lshl_add_u64 v[12:13], v[160:161], 2, s[4:5]
	s_nop 0
	s_nop 0
	ds_read_b32 v74, v173 offset:4096
	s_waitcnt lgkmcnt(0)
	v_pk_mul_f32 v[22:23], v[22:23], v[74:75] op_sel_hi:[1,0]
	v_pk_mul_f32 v[20:21], v[20:21], v[74:75] op_sel_hi:[1,0]
	v_pk_mul_f32 v[30:31], v[30:31], v[74:75] op_sel_hi:[1,0]
	v_pk_mul_f32 v[28:29], v[28:29], v[74:75] op_sel_hi:[1,0]
	v_pk_add_f32 v[10:11], v[198:199], 1.0 op_sel_hi:[1,0]
	v_pk_add_f32 v[8:9], v[196:197], 1.0 op_sel_hi:[1,0]
	v_pk_add_f32 v[14:15], v[202:203], 1.0 op_sel_hi:[1,0]
	v_pk_add_f32 v[12:13], v[200:201], 1.0 op_sel_hi:[1,0]
	v_pk_mul_f32 v[42:43], v[206:207], v[10:11]
	v_pk_mul_f32 v[40:41], v[204:205], v[8:9]
	v_pk_mul_f32 v[14:15], v[210:211], v[14:15]
	v_pk_mul_f32 v[12:13], v[208:209], v[12:13]
	v_pk_fma_f32 v[10:11], v[42:43], v[22:23], v[224:225]
	v_pk_fma_f32 v[8:9], v[40:41], v[20:21], v[222:223]
	v_pk_fma_f32 v[20:21], v[14:15], v[30:31], v[228:229]
	v_pk_fma_f32 v[22:23], v[12:13], v[28:29], v[226:227]
	v_cvt_pk_bf16_f32 v8, v8, v9
	v_cvt_pk_bf16_f32 v9, v10, v11
	v_cvt_pk_bf16_f32 v10, v22, v23
	v_cvt_pk_bf16_f32 v11, v20, v21
	global_store_dwordx4 v[56:57], v[8:11], off offset:256
	ds_read_b32 v8, v173 offset:4160
	s_waitcnt lgkmcnt(0)
;     __device__ __forceinline__ void operator()(AccT& acc, const pg8::Unit& u, int wr, int wc, int fr_, int fq_) const {
;     ...
; #pragma unroll
;             for (int ai = 0; ai < 2; ++ai)
; #pragma unroll
;                 for (int m = 0; m < 4; ++m) { const int rl = ai * 128 + wr * 64 + m * 16 + fr; const size_t row = (size_t)u.pm * 256 + rl; const float rstd = sred[1024 + rl];
;                     const f32x4 y0 = acc[ai][bj][m][0] * rstd * a0 + b0, y1 = acc[ai][bj][m][1] * rstd * a1 + b1;
;                     if (MODE == 0) *(bf16x8*)(Hout + row * D + col) = pack8(y0[0], y0[1], y0[2], y0[3], y1[0], y1[1], y1[2], y1[3]);
;                     else { __builtin_nontemporal_store(y0, (f32x4*)(X + row * D + col)); __builtin_nontemporal_store(y1, (f32x4*)(X + row * D + col + 4)); }
;                     __builtin_amdgcn_sched_barrier(0); }
;         }
;         __syncthreads();
	v_pk_mul_f32 v[10:11], v[38:39], v[8:9] op_sel_hi:[1,0]
	v_pk_mul_f32 v[20:21], v[36:37], v[8:9] op_sel_hi:[1,0]
	v_pk_mul_f32 v[22:23], v[50:51], v[8:9] op_sel_hi:[1,0]
	v_pk_mul_f32 v[8:9], v[48:49], v[8:9] op_sel_hi:[1,0]
	v_pk_fma_f32 v[10:11], v[42:43], v[10:11], v[224:225]
	v_pk_fma_f32 v[20:21], v[40:41], v[20:21], v[222:223]
	v_pk_fma_f32 v[22:23], v[14:15], v[22:23], v[228:229]
	v_pk_fma_f32 v[28:29], v[12:13], v[8:9], v[226:227]
	v_cvt_pk_bf16_f32 v8, v20, v21
	v_cvt_pk_bf16_f32 v9, v10, v11
	v_cvt_pk_bf16_f32 v10, v28, v29
	v_cvt_pk_bf16_f32 v11, v22, v23
	global_store_dwordx4 v[58:59], v[8:11], off offset:256
	ds_read_b32 v8, v173 offset:4224
	s_waitcnt lgkmcnt(0)
	v_pk_mul_f32 v[10:11], v[62:63], v[8:9] op_sel_hi:[1,0]
	v_pk_mul_f32 v[20:21], v[60:61], v[8:9] op_sel_hi:[1,0]
	v_pk_mul_f32 v[22:23], v[82:83], v[8:9] op_sel_hi:[1,0]
	v_pk_mul_f32 v[8:9], v[80:81], v[8:9] op_sel_hi:[1,0]
	v_pk_fma_f32 v[10:11], v[42:43], v[10:11], v[224:225]
	v_pk_fma_f32 v[20:21], v[40:41], v[20:21], v[222:223]
	v_pk_fma_f32 v[22:23], v[14:15], v[22:23], v[228:229]
	v_pk_fma_f32 v[28:29], v[12:13], v[8:9], v[226:227]
	v_cvt_pk_bf16_f32 v8, v20, v21
	v_cvt_pk_bf16_f32 v9, v10, v11
	v_cvt_pk_bf16_f32 v10, v28, v29
	v_cvt_pk_bf16_f32 v11, v22, v23
	global_store_dwordx4 v[64:65], v[8:11], off offset:256
	ds_read_b32 v8, v173 offset:4288
	s_waitcnt lgkmcnt(0)
	v_pk_mul_f32 v[10:11], v[98:99], v[8:9] op_sel_hi:[1,0]
	v_pk_mul_f32 v[20:21], v[96:97], v[8:9] op_sel_hi:[1,0]
	v_pk_mul_f32 v[22:23], v[106:107], v[8:9] op_sel_hi:[1,0]
	v_pk_mul_f32 v[8:9], v[104:105], v[8:9] op_sel_hi:[1,0]
	v_pk_fma_f32 v[10:11], v[42:43], v[10:11], v[224:225]
	v_pk_fma_f32 v[20:21], v[40:41], v[20:21], v[222:223]
	v_pk_fma_f32 v[22:23], v[14:15], v[22:23], v[228:229]
	v_pk_fma_f32 v[28:29], v[12:13], v[8:9], v[226:227]
	v_cvt_pk_bf16_f32 v8, v20, v21
	v_cvt_pk_bf16_f32 v9, v10, v11
	v_cvt_pk_bf16_f32 v10, v28, v29
	v_cvt_pk_bf16_f32 v11, v22, v23
	global_store_dwordx4 v[66:67], v[8:11], off offset:256
	ds_read_b32 v8, v173 offset:4608
	s_waitcnt lgkmcnt(0)
	v_pk_mul_f32 v[10:11], v[90:91], v[8:9] op_sel_hi:[1,0]
	v_pk_mul_f32 v[20:21], v[88:89], v[8:9] op_sel_hi:[1,0]
	v_pk_mul_f32 v[22:23], v[78:79], v[8:9] op_sel_hi:[1,0]
	v_pk_mul_f32 v[8:9], v[76:77], v[8:9] op_sel_hi:[1,0]
	v_pk_fma_f32 v[10:11], v[42:43], v[10:11], v[224:225]
	v_pk_fma_f32 v[20:21], v[40:41], v[20:21], v[222:223]
	v_pk_fma_f32 v[22:23], v[14:15], v[22:23], v[228:229]
	v_pk_fma_f32 v[28:29], v[12:13], v[8:9], v[226:227]
	v_cvt_pk_bf16_f32 v8, v20, v21
	v_cvt_pk_bf16_f32 v9, v10, v11
	v_cvt_pk_bf16_f32 v10, v28, v29
	v_cvt_pk_bf16_f32 v11, v22, v23
	global_store_dwordx4 v[84:85], v[8:11], off offset:256
	ds_read_b32 v8, v173 offset:4672
	s_waitcnt lgkmcnt(0)
	v_pk_mul_f32 v[10:11], v[54:55], v[8:9] op_sel_hi:[1,0]
	v_pk_mul_f32 v[20:21], v[52:53], v[8:9] op_sel_hi:[1,0]
	v_pk_mul_f32 v[22:23], v[46:47], v[8:9] op_sel_hi:[1,0]
	v_pk_mul_f32 v[8:9], v[44:45], v[8:9] op_sel_hi:[1,0]
	v_pk_fma_f32 v[10:11], v[42:43], v[10:11], v[224:225]
	v_pk_fma_f32 v[20:21], v[40:41], v[20:21], v[222:223]
	v_pk_fma_f32 v[22:23], v[14:15], v[22:23], v[228:229]
	v_pk_fma_f32 v[28:29], v[12:13], v[8:9], v[226:227]
	v_cvt_pk_bf16_f32 v8, v20, v21
	v_cvt_pk_bf16_f32 v9, v10, v11
	v_cvt_pk_bf16_f32 v10, v28, v29
	v_cvt_pk_bf16_f32 v11, v22, v23
	global_store_dwordx4 v[68:69], v[8:11], off offset:256
	ds_read_b32 v8, v173 offset:4736
	s_waitcnt lgkmcnt(0)
	v_pk_mul_f32 v[10:11], v[26:27], v[8:9] op_sel_hi:[1,0]
	v_pk_mul_f32 v[20:21], v[24:25], v[8:9] op_sel_hi:[1,0]
	v_pk_mul_f32 v[18:19], v[18:19], v[8:9] op_sel_hi:[1,0]
	v_pk_mul_f32 v[8:9], v[16:17], v[8:9] op_sel_hi:[1,0]
	v_pk_fma_f32 v[10:11], v[42:43], v[10:11], v[224:225]
	v_pk_fma_f32 v[16:17], v[40:41], v[20:21], v[222:223]
	v_pk_fma_f32 v[18:19], v[14:15], v[18:19], v[228:229]
	v_pk_fma_f32 v[20:21], v[12:13], v[8:9], v[226:227]
	v_cvt_pk_bf16_f32 v8, v16, v17
	v_cvt_pk_bf16_f32 v9, v10, v11
	v_cvt_pk_bf16_f32 v10, v20, v21
	v_cvt_pk_bf16_f32 v11, v18, v19
	global_store_dwordx4 v[32:33], v[8:11], off offset:256
	ds_read_b32 v8, v173 offset:4800
	s_waitcnt lgkmcnt(0)
	v_pk_mul_f32 v[6:7], v[6:7], v[8:9] op_sel_hi:[1,0]
	v_pk_mul_f32 v[4:5], v[4:5], v[8:9] op_sel_hi:[1,0]
	v_pk_mul_f32 v[2:3], v[2:3], v[8:9] op_sel_hi:[1,0]
	v_pk_mul_f32 v[0:1], v[0:1], v[8:9] op_sel_hi:[1,0]
	v_pk_fma_f32 v[6:7], v[42:43], v[6:7], v[224:225]
	v_pk_fma_f32 v[4:5], v[40:41], v[4:5], v[222:223]
	v_pk_fma_f32 v[8:9], v[14:15], v[2:3], v[228:229]
	v_pk_fma_f32 v[2:3], v[12:13], v[0:1], v[226:227]
	v_cvt_pk_bf16_f32 v0, v4, v5
	v_cvt_pk_bf16_f32 v1, v6, v7
	v_cvt_pk_bf16_f32 v2, v2, v3
	v_cvt_pk_bf16_f32 v3, v8, v9
	global_store_dwordx4 v[34:35], v[0:3], off offset:256
	s_andn2_b64 vcc, exec, s[8:9]
	s_mov_b64 s[4:5], -1
	s_barrier
	s_cbranch_vccnz .LBB0_2006
	s_andn2_b64 vcc, exec, s[20:21]
	s_cbranch_vccnz .LBB0_2005
	s_barrier
	s_branch .LBB0_2005
